# P1 in-proj GEMM: column-tile index permuted (blocks of 4) so each WG's units mix cheap and expensive epilogue segments
# baseline (speedup 1.0000x reference)
.LBB0_85:
.LBB0_86:
	s_cmp_lt_i32 s72, 2
	s_cselect_b64 s[4:5], -1, 0
	s_add_u32 s20, s70, 0x2100000
	s_addc_u32 s21, s71, 0
	s_add_u32 s16, s70, 0x2900000
	s_addc_u32 s17, s71, 0
	s_add_u32 s8, s70, 0x2b00000
	s_addc_u32 s9, s71, 0
	v_writelane_b32 v242, s8, 47
	s_nop 1
	v_writelane_b32 v242, s9, 48
	s_add_u32 s8, s70, 0x3300000
	s_addc_u32 s9, s71, 0
	s_add_u32 s92, s70, 0x9300000
	s_addc_u32 s93, s71, 0
	s_add_u32 s97, s70, 0xc000000
	s_addc_u32 s33, s71, 0
	s_add_u32 s38, s70, 0x14800000
	v_writelane_b32 v242, s8, 49
	s_addc_u32 s39, s71, 0
	s_mov_b32 s96, s33
	v_writelane_b32 v242, s9, 50
	s_add_u32 s8, s70, 0x1d000000
	s_addc_u32 s9, s71, 0
	v_writelane_b32 v242, s8, 51
	s_nop 1
	v_writelane_b32 v242, s9, 52
	s_and_b64 s[8:9], s[4:5], s[0:1]
	s_andn2_b64 vcc, exec, s[8:9]
	s_cbranch_vccnz .LBB0_176
	s_cmpk_lt_i32 s2, 0x440
	s_cselect_b64 s[0:1], -1, 0
	s_cmpk_gt_i32 s2, 0x43f
	v_readfirstlane_b32 s22, v143
	s_cbranch_scc1 .LBB0_90
	s_ashr_i32 s3, s2, 31
	s_lshr_b32 s3, s3, 29
	s_add_i32 s3, s2, s3
	s_ashr_i32 s4, s3, 3
	s_and_b32 s3, s3, -8
	s_sub_i32 s3, s2, s3
	s_cmp_lt_i32 s3, 0
	s_movk_i32 s5, 0x89
	s_cselect_b32 s5, s5, 0x88
	s_mul_i32 s3, s3, s5
	s_add_i32 s3, s3, s4
	s_ashr_i32 s4, s3, 31
	s_lshr_b32 s4, s4, 24
	s_add_i32 s4, s3, s4
	s_ashr_i32 s4, s4, 8
	s_lshl_b32 s10, s4, 3
	s_sub_i32 s5, 34, s10
	s_lshl_b32 s4, s4, 8
	s_min_u32 s11, s5, 8
	s_sub_i32 s3, s3, s4
	s_sext_i32_i16 s4, s3
	v_cvt_f32_ubyte0_e32 v2, s11
	v_cvt_f32_i32_e32 v1, s4
	v_rcp_iflag_f32_e32 v3, v2
	s_ashr_i32 s4, s4, 30
	s_or_b32 s12, s4, 1
	v_mul_f32_e32 v3, v1, v3
	v_trunc_f32_e32 v3, v3
	v_fma_f32 v1, -v3, v2, v1
	v_cvt_i32_f32_e32 v3, v3
	v_cmp_ge_f32_e64 s[4:5], |v1|, v2
	s_and_b64 s[4:5], s[4:5], exec
	s_cselect_b32 s4, s12, 0
	v_readfirstlane_b32 s5, v3
	s_add_i32 s5, s5, s4
	s_sext_i32_i16 s4, s5
	s_mul_i32 s5, s5, s11
	s_sub_i32 s3, s3, s5
	s_sext_i32_i16 s3, s3
	s_add_i32 s34, s10, s3
	s_and_b32 s3, s4, 28
	s_lshr_b32 s5, 0x53472610, s3
	s_and_b32 s5, s5, 7
	s_lshl_b32 s5, s5, 2
	s_and_b32 s4, s4, 3
	s_or_b32 s4, s4, s5
	s_andn2_b64 vcc, exec, s[0:1]
	s_cbranch_vccz .LBB0_91

.LBB0_96:
	s_add_i32 s46, s46, 1
	s_mul_i32 s0, s46, s49
	s_mul_hi_u32 s1, s46, s50
	s_add_i32 s1, s1, s0
	s_mul_i32 s0, s46, s50
	s_add_u32 s28, s0, s2
	s_addc_u32 s29, s1, s51
	v_cmp_gt_i64_e32 vcc, s[28:29], v[156:157]
	v_cmp_lt_i64_e64 s[0:1], s[28:29], v[154:155]
	s_cbranch_vccnz .LBB0_98
	s_ashr_i32 s5, s28, 31
	s_lshr_b32 s5, s5, 29
	s_add_i32 s5, s28, s5
	s_ashr_i32 s24, s5, 3
	s_and_b32 s5, s5, -8
	s_sub_i32 s5, s28, s5
	s_cmp_lt_i32 s5, 0
	s_movk_i32 s25, 0x89
	s_cselect_b32 s25, s25, 0x88
	s_mul_i32 s5, s5, s25
	s_add_i32 s5, s5, s24
	s_ashr_i32 s24, s5, 31
	s_lshr_b32 s24, s24, 24
	s_add_i32 s24, s5, s24
	s_ashr_i32 s25, s24, 8
	s_lshl_b32 s25, s25, 3
	s_sub_i32 s26, 34, s25
	s_min_i32 s26, s26, 8
	s_abs_i32 s27, s26
	v_cvt_f32_u32_e32 v2, s27
	s_sub_i32 s29, 0, s27
	s_and_b32 s24, s24, 0xffffff00
	s_sub_i32 s5, s5, s24
	v_rcp_iflag_f32_e32 v2, v2
	s_abs_i32 s24, s5
	s_xor_b32 s28, s5, s26
	s_ashr_i32 s28, s28, 31
	v_mul_f32_e32 v2, 0x4f7ffffe, v2
	v_cvt_u32_f32_e32 v2, v2
	s_nop 0
	v_readfirstlane_b32 s30, v2
	s_mul_i32 s29, s29, s30
	s_mul_hi_u32 s29, s30, s29
	s_add_i32 s30, s30, s29
	s_mul_hi_u32 s29, s24, s30
	s_mul_i32 s30, s29, s27
	s_sub_i32 s24, s24, s30
	s_add_i32 s31, s29, 1
	s_sub_i32 s30, s24, s27
	s_cmp_ge_u32 s24, s27
	s_cselect_b32 s29, s31, s29
	s_cselect_b32 s24, s30, s24
	s_add_i32 s30, s29, 1
	s_cmp_ge_u32 s24, s27
	s_cselect_b32 s24, s30, s29
	s_xor_b32 s24, s24, s28
	s_sub_i32 s24, s24, s28
	s_mul_i32 s26, s24, s26
	s_sub_i32 s5, s5, s26
	s_add_i32 s26, s25, s5
	s_and_b32 s5, s24, 28
	s_lshr_b32 s25, 0x53472610, s5
	s_and_b32 s25, s25, 7
	s_lshl_b32 s25, s25, 2
	s_and_b32 s24, s24, 3
	s_or_b32 s24, s24, s25
